# XCC-local barriers: arrive = plain store of generation into per-XCC flag line, wait = one 32-lane sc1 load per poll (replaces returning atomics + generation word)
# speedup vs baseline: 1.0060x; 1.0060x over previous
; #define LAS __attribute__((address_space(3)))
; __device__ __forceinline__ int otid(int wave) { return wave * 64 + olane(); }
; __device__ __forceinline__ unsigned xb_ld(unsigned* p)              { return __hip_atomic_load(p, __ATOMIC_RELAXED, __HIP_MEMORY_SCOPE_AGENT); }
; #define XB_SPIN(cond, bar) do { unsigned _sp = 0; while (cond) { __builtin_amdgcn_s_sleep(1); \
;     if ((++_sp & 255u) == 0u) { if (xb_ld(&(bar)[XB_TMO])) break; if (_sp > XB_SPIN_CAP) { atomicAdd(&(bar)[XB_TMO], 1u); break; } } } } while (0)
; __device__ __forceinline__ bool is_t0(int wave) { return wave == 0 && olane() == 0; }
; __device__ __forceinline__ void xcdl_wait_t0(const XcdBarrier& b) {
;     if (is_t0(b.wave)) {
;         unsigned* bar = b.bar; asm volatile("" : "+s"(bar));
;         const unsigned gen = b.st[5];
;         XB_SPIN(xb_ld(&bar[XB_LGEN(b.x)]) == gen, bar);
;         __builtin_amdgcn_fence(__ATOMIC_ACQUIRE, "agent");
;         asm volatile("s_waitcnt vmcnt(0)" ::: "memory");
;     }
; }
; __global__ void __launch_bounds__(512, 2) mk_fwd(Args args) {
;     ...
;                 LAS float* lb = (LAS float*)(F.lds + 131072); P.lbias = lb; const int t_ = otid(F.wave);
; #pragma unroll
;                 for (int i = 0; i < 4; ++i) { const int e = i * 512 + t_, slot = e >> 8; const int pn_ = (P1_MAP == 1) ? (((cid >> 3) & 7) + 8 * (slot & 3)) : (4 * slot + (cid >> 6)); lb[e] = P.biasp[256 * pn_ + (e & 255)]; }
;                 if (splitb && (SPLIT_BAR & 2) && L > 0) xcdl_wait_t0(bar);
;                 if (psync && (PSYNC & 2) && L > 0) psync_wait((unsigned*)(ctl + CW_PSYNC + (2 * (L - 1) + 1) * 1024 + 16 * (8 * (cid & 7) + ((cid >> 3) & 7))), (unsigned*)(ctl + CW_TMO), 0x910u);
;                 __syncthreads(); }
.LBB0_174:
	s_lshl_b32 s34, s58, 2
	s_or_b32 s2, s34, 1
	s_cmp_le_i32 s66, s2
	s_cselect_b64 s[0:1], -1, 0
	s_cmp_lt_i32 s2, s67
	s_cselect_b64 s[2:3], -1, 0
	v_writelane_b32 v254, s60, 52
	s_and_b64 s[2:3], s[0:1], s[2:3]
	s_andn2_b64 vcc, exec, s[2:3]
	v_writelane_b32 v254, s61, 53
	v_writelane_b32 v254, s34, 54
	s_cbranch_vccnz .LBB0_398
	v_readlane_b32 s0, v254, 11
	s_mov_b64 s[42:43], s[82:83]
	v_readlane_b32 s1, v254, 12
	s_lshl_b32 s78, s58, 13
	v_mbcnt_lo_u32_b32 v0, -1, 0
	v_mbcnt_hi_u32_b32 v0, -1, v0
	s_and_b64 s[0:1], s[88:89], s[0:1]
	v_add_u32_e32 v2, s70, v0
	s_lshl_b64 s[6:7], s[78:79], 2
	v_lshrrev_b32_e32 v0, 6, v2
	s_add_u32 s6, s42, s6
	v_and_b32_e32 v0, 0xfffffc, v0
	v_readlane_b32 s8, v253, 7
	s_addc_u32 s7, s43, s7
	v_and_b32_e32 v3, 0xff, v2
	v_add_u32_e32 v0, s8, v0
	s_add_u32 s6, s6, 0x1d80000
	v_lshl_or_b32 v0, v0, 8, v3
	s_addc_u32 s7, s7, 0
	v_ashrrev_i32_e32 v1, 31, v0
	v_lshl_add_u64 v[0:1], v[0:1], 2, s[6:7]
	flat_load_dword v4, v[0:1]
	v_lshl_add_u32 v0, v2, 2, 0
	v_add_u32_e32 v1, 0x200, v2
	v_add_u32_e32 v5, 0x20000, v0
	v_lshrrev_b32_e32 v0, 6, v1
	v_and_b32_e32 v0, 0xfffffc, v0
	v_add_u32_e32 v0, s8, v0
	v_lshl_or_b32 v0, v0, 8, v3
	v_ashrrev_i32_e32 v1, 31, v0
	v_lshl_add_u64 v[0:1], v[0:1], 2, s[6:7]
	s_andn2_b64 vcc, exec, s[0:1]
	flat_load_dword v6, v[0:1]
	v_add_u32_e32 v0, 0x400, v2
	v_lshrrev_b32_e32 v0, 6, v0
	v_and_b32_e32 v0, 0xfffffc, v0
	v_add_u32_e32 v0, s8, v0
	v_lshl_or_b32 v0, v0, 8, v3
	v_ashrrev_i32_e32 v1, 31, v0
	v_lshl_add_u64 v[0:1], v[0:1], 2, s[6:7]
	flat_load_dword v7, v[0:1]
	v_add_u32_e32 v0, 0x600, v2
	v_lshrrev_b32_e32 v0, 6, v0
	v_and_b32_e32 v0, 0xfffffc, v0
	v_add_u32_e32 v0, s8, v0
	v_lshl_or_b32 v0, v0, 8, v3
	v_ashrrev_i32_e32 v1, 31, v0
	v_lshl_add_u64 v[0:1], v[0:1], 2, s[6:7]
	flat_load_dword v8, v[0:1]
	s_nop 0
	s_nop 0
	s_nop 0
	s_waitcnt vmcnt(0) lgkmcnt(0)
	ds_write_b32 v5, v4
	ds_write_b32 v5, v6 offset:2048
	ds_write_b32 v5, v7 offset:4096
	ds_write_b32 v5, v8 offset:6144
	s_cbranch_vccnz .LBB0_190
	v_mbcnt_lo_u32_b32 v0, -1, 0
	v_mbcnt_hi_u32_b32 v0, -1, v0
	s_nop 0
	v_cmp_eq_u32_e32 vcc, 0, v0
	s_and_saveexec_b64 s[6:7], vcc
	s_cbranch_execz .LBB0_189
	s_lshl_b32 s16, s23, 1
	s_add_u32 s0, s26, 0x6000
	s_addc_u32 s1, s27, 0
	s_add_u32 s0, s0, s16
	s_addc_u32 s1, s1, 0
	v_mov_b32_e32 v0, s21
	ds_read_b32 v0, v0
	s_waitcnt vmcnt(0) lgkmcnt(0)
	v_readfirstlane_b32 s8, v0
	s_mov_b64 s[10:11], exec
	s_mov_b32 exec_lo, -1
	s_mov_b32 exec_hi, 0
	v_mbcnt_lo_u32_b32 v2, -1, 0
	v_lshlrev_b32_e32 v2, 2, v2
	v_mov_b32_e32 v1, s8
	s_mov_b32 s9, 0
.Lxbf_poll_S5:
	global_load_dword v3, v2, s[0:1] sc1
	s_waitcnt vmcnt(0)
	v_cmp_lt_u32_e32 vcc, v3, v1
	s_nop 1
	s_cmp_eq_u64 vcc, 0
	s_cbranch_scc1 .Lxbf_done_S5
	s_sleep 1
	s_add_u32 s9, s9, 1
	s_cmp_lt_u32 s9, 0x4000
	s_cbranch_scc1 .Lxbf_poll_S5
	v_mov_b32_e32 v3, 1
	v_mov_b32_e32 v2, 0x200
	global_store_dword v2, v3, s[26:27] sc1
.Lxbf_done_S5:
	s_waitcnt vmcnt(0)
	s_mov_b64 exec, s[10:11]
	s_branch .Lxbf_end_S5
	s_nop 0
	s_nop 0
	s_nop 0
	s_nop 0
	s_nop 0
	s_nop 0
	s_nop 0
	s_nop 0
	s_nop 0
	s_nop 0
	s_nop 0
	s_nop 0
	s_nop 0
	s_nop 0
	s_nop 0
	s_nop 0
	s_nop 0
	s_nop 0
	s_nop 0
	s_nop 0
	s_nop 0
	s_nop 0
	s_nop 0
	s_nop 0
	s_nop 0
	s_nop 0
	s_nop 0
	s_nop 0
	s_nop 0
	s_nop 0
	s_nop 0
	s_nop 0
	s_nop 0
	s_nop 0
	s_nop 0
	s_nop 0
	s_nop 0
	s_nop 0
	s_nop 0
	s_nop 0
	s_nop 0
	s_nop 0
.Lxbf_end_S5:
.LBB0_189:
	s_or_b64 exec, exec, s[6:7]

; __device__ __forceinline__ unsigned xb_ld(unsigned* p)              { return __hip_atomic_load(p, __ATOMIC_RELAXED, __HIP_MEMORY_SCOPE_AGENT); }
; __device__ __forceinline__ unsigned xb_add(unsigned* p, unsigned v) { return __hip_atomic_fetch_add(p, v, __ATOMIC_RELAXED, __HIP_MEMORY_SCOPE_AGENT); }
; #define XB_SPIN(cond, bar) do { unsigned _sp = 0; while (cond) { __builtin_amdgcn_s_sleep(1); \
;     if ((++_sp & 255u) == 0u) { if (xb_ld(&(bar)[XB_TMO])) break; if (_sp > XB_SPIN_CAP) { atomicAdd(&(bar)[XB_TMO], 1u); break; } } } } while (0)
; __device__ __forceinline__ bool is_t0(int wave) { return wave == 0 && olane() == 0; }
; __device__ __forceinline__ void xcdl_barrier(const XcdBarrier& b) {
;     asm volatile("s_waitcnt vmcnt(0)" ::: "memory");
;     __syncthreads();
;     if (is_t0(b.wave)) {
;         unsigned* bar = b.bar; asm volatile("" : "+s"(bar));
;         __builtin_amdgcn_s_waitcnt(0);
;         const unsigned old = xb_add(&bar[XB_LSUB(b.x)], 1u);
;         const unsigned gen = old >> 5;
;         if ((old & 31u) == 31u) xb_add(&bar[XB_LGEN(b.x)], 1u);
;         else XB_SPIN(xb_ld(&bar[XB_LGEN(b.x)]) == gen, bar);
;         __builtin_amdgcn_fence(__ATOMIC_ACQUIRE, "agent");
;         asm volatile("s_waitcnt vmcnt(0)" ::: "memory");
;     }
;     __syncthreads();
; }
.LBB0_447:
	s_and_b64 vcc, exec, s[0:1]
	s_cbranch_vccz .LBB0_467
	s_waitcnt vmcnt(0)
	s_and_b64 vcc, exec, s[46:47]
	s_waitcnt vmcnt(0)
	s_barrier
	s_cbranch_vccnz .LBB0_466
	v_mbcnt_lo_u32_b32 v0, -1, 0
	v_mbcnt_hi_u32_b32 v0, -1, v0
	s_nop 0
	v_cmp_eq_u32_e32 vcc, 0, v0
	s_and_saveexec_b64 s[2:3], vcc
	s_cbranch_execz .LBB0_465
	s_lshl_b32 s6, s23, 1
	s_add_u32 s0, s26, 0x6000
	s_addc_u32 s1, s27, 0
	s_add_u32 s0, s0, s6
	s_addc_u32 s1, s1, 0
	v_readlane_b32 s6, v254, 49
	s_add_i32 s7, s34, 1
	s_lshr_b32 s6, s6, 3
	s_lshl_b32 s6, s6, 2
	v_mov_b32_e32 v0, s6
	v_mov_b32_e32 v1, s7
	s_waitcnt vmcnt(0) lgkmcnt(0)
	global_store_dword v0, v1, s[0:1]
	s_mov_b64 s[28:29], exec
	s_mov_b32 exec_lo, -1
	s_mov_b32 exec_hi, 0
	v_mbcnt_lo_u32_b32 v2, -1, 0
	v_lshlrev_b32_e32 v2, 2, v2
	v_mov_b32_e32 v1, s7
	s_mov_b32 s8, 0
.Lxbf_poll_S1:
	global_load_dword v3, v2, s[0:1] sc1
	s_waitcnt vmcnt(0)
	v_cmp_lt_u32_e32 vcc, v3, v1
	s_nop 1
	s_cmp_eq_u64 vcc, 0
	s_cbranch_scc1 .Lxbf_done_S1
	s_sleep 1
	s_add_u32 s8, s8, 1
	s_cmp_lt_u32 s8, 0x4000
	s_cbranch_scc1 .Lxbf_poll_S1
	v_mov_b32_e32 v3, 1
	v_mov_b32_e32 v2, 0x200
	global_store_dword v2, v3, s[26:27] sc1
.Lxbf_done_S1:
	s_waitcnt vmcnt(0)
	s_mov_b64 exec, s[28:29]

; __device__ __forceinline__ unsigned xb_ld(unsigned* p)              { return __hip_atomic_load(p, __ATOMIC_RELAXED, __HIP_MEMORY_SCOPE_AGENT); }
; __device__ __forceinline__ unsigned xb_add(unsigned* p, unsigned v) { return __hip_atomic_fetch_add(p, v, __ATOMIC_RELAXED, __HIP_MEMORY_SCOPE_AGENT); }
; #define XB_SPIN(cond, bar) do { unsigned _sp = 0; while (cond) { __builtin_amdgcn_s_sleep(1); \
;     if ((++_sp & 255u) == 0u) { if (xb_ld(&(bar)[XB_TMO])) break; if (_sp > XB_SPIN_CAP) { atomicAdd(&(bar)[XB_TMO], 1u); break; } } } } while (0)
; __device__ __forceinline__ bool is_t0(int wave) { return wave == 0 && olane() == 0; }
; __device__ __forceinline__ void xcdl_barrier(const XcdBarrier& b) {
;     asm volatile("s_waitcnt vmcnt(0)" ::: "memory");
;     __syncthreads();
;     if (is_t0(b.wave)) {
;         unsigned* bar = b.bar; asm volatile("" : "+s"(bar));
;         __builtin_amdgcn_s_waitcnt(0);
;         const unsigned old = xb_add(&bar[XB_LSUB(b.x)], 1u);
;         const unsigned gen = old >> 5;
;         if ((old & 31u) == 31u) xb_add(&bar[XB_LGEN(b.x)], 1u);
;         else XB_SPIN(xb_ld(&bar[XB_LGEN(b.x)]) == gen, bar);
.LBB0_611:
	s_and_b64 vcc, exec, s[0:1]
	s_cbranch_vccz .LBB0_631
	s_waitcnt vmcnt(0)
	s_and_b64 vcc, exec, s[46:47]
	s_waitcnt vmcnt(0)
	s_barrier
	s_cbranch_vccnz .LBB0_630
	v_mbcnt_lo_u32_b32 v0, -1, 0
	v_mbcnt_hi_u32_b32 v0, -1, v0
	s_nop 0
	v_cmp_eq_u32_e32 vcc, 0, v0
	s_and_saveexec_b64 s[4:5], vcc
	s_cbranch_execz .LBB0_629
	s_lshl_b32 s6, s23, 1
	s_add_u32 s0, s26, 0x6000
	s_addc_u32 s1, s27, 0
	s_add_u32 s0, s0, s6
	s_addc_u32 s1, s1, 0
	v_readlane_b32 s6, v254, 49
	s_add_i32 s7, s34, 2
	s_lshr_b32 s6, s6, 3
	s_lshl_b32 s6, s6, 2
	v_mov_b32_e32 v0, s6
	v_mov_b32_e32 v1, s7
	s_waitcnt vmcnt(0) lgkmcnt(0)
	global_store_dword v0, v1, s[0:1]
	s_mov_b64 s[10:11], exec
	s_mov_b32 exec_lo, -1
	s_mov_b32 exec_hi, 0
	v_mbcnt_lo_u32_b32 v2, -1, 0
	v_lshlrev_b32_e32 v2, 2, v2
	v_mov_b32_e32 v1, s7
	s_mov_b32 s8, 0

; __device__ __forceinline__ unsigned xb_ld(unsigned* p)              { return __hip_atomic_load(p, __ATOMIC_RELAXED, __HIP_MEMORY_SCOPE_AGENT); }
; __device__ __forceinline__ unsigned xb_add(unsigned* p, unsigned v) { return __hip_atomic_fetch_add(p, v, __ATOMIC_RELAXED, __HIP_MEMORY_SCOPE_AGENT); }
; #define XB_SPIN(cond, bar) do { unsigned _sp = 0; while (cond) { __builtin_amdgcn_s_sleep(1); \
;     if ((++_sp & 255u) == 0u) { if (xb_ld(&(bar)[XB_TMO])) break; if (_sp > XB_SPIN_CAP) { atomicAdd(&(bar)[XB_TMO], 1u); break; } } } } while (0)
; __device__ __forceinline__ void xcdl_barrier(const XcdBarrier& b) {
;     ...
;         const unsigned gen = old >> 5;
;         if ((old & 31u) == 31u) xb_add(&bar[XB_LGEN(b.x)], 1u);
;         else XB_SPIN(xb_ld(&bar[XB_LGEN(b.x)]) == gen, bar);
;         __builtin_amdgcn_fence(__ATOMIC_ACQUIRE, "agent");
;         asm volatile("s_waitcnt vmcnt(0)" ::: "memory");
;     }
;     __syncthreads();
.Lxbf_done_S2:
	buffer_inv sc1
	s_waitcnt vmcnt(0)
	s_mov_b64 exec, s[10:11]
	s_branch .Lxbf_end_S2
	s_nop 0
	s_nop 0
	s_nop 0
	s_nop 0
	s_nop 0
	s_nop 0
	s_nop 0
	s_nop 0
	s_nop 0
	s_nop 0
	s_nop 0
	s_nop 0
	s_nop 0
	s_nop 0
	s_nop 0
	s_nop 0
	s_nop 0
	s_nop 0
	s_nop 0
	s_nop 0
	s_nop 0
	s_nop 0
	s_nop 0
	s_nop 0
	s_nop 0
	s_nop 0
	s_nop 0
	s_nop 0
	s_nop 0
	s_nop 0
	s_nop 0
	s_nop 0
	s_nop 0
	s_nop 0
	s_nop 0
	s_nop 0
	s_nop 0
	s_nop 0
	s_nop 0
	s_nop 0
	s_nop 0
	s_nop 0
	s_nop 0
	s_nop 0
	s_nop 0
	s_nop 0
	s_nop 0
	s_nop 0
	s_nop 0
	s_nop 0
	s_nop 0
	s_nop 0
	s_nop 0
	s_nop 0
	s_nop 0
	s_nop 0
	s_nop 0
	s_nop 0
	s_nop 0
	s_nop 0
	s_nop 0
	s_nop 0
	s_nop 0
	s_nop 0
	s_nop 0
	s_nop 0
	s_nop 0
	s_nop 0
	s_nop 0
	s_nop 0
	s_nop 0
	s_nop 0
	s_nop 0
	s_nop 0
	s_nop 0
	s_nop 0
	s_nop 0
	s_nop 0
	s_nop 0
	s_nop 0
	s_nop 0
	s_nop 0
	s_nop 0
	s_nop 0
	s_nop 0
	s_nop 0
	s_nop 0
	s_nop 0
	s_nop 0
	s_nop 0
	s_nop 0
	s_nop 0
	s_nop 0
	s_nop 0
	s_nop 0
	s_nop 0
	s_nop 0
	s_nop 0
	s_nop 0
	s_nop 0
	s_nop 0
	s_nop 0
	s_nop 0
	s_nop 0
	s_nop 0
	s_nop 0
	s_nop 0
	s_nop 0
	s_nop 0
.Lxbf_end_S2:
.LBB0_629:
	s_or_b64 exec, exec, s[4:5]

; __device__ __forceinline__ unsigned xb_add(unsigned* p, unsigned v) { return __hip_atomic_fetch_add(p, v, __ATOMIC_RELAXED, __HIP_MEMORY_SCOPE_AGENT); }
; __device__ __forceinline__ bool is_t0(int wave) { return wave == 0 && olane() == 0; }
; __device__ __forceinline__ void xcdl_arrive(const XcdBarrier& b) {
;     if (is_t0(b.wave)) {
;         unsigned* bar = b.bar; asm volatile("" : "+s"(bar));
;         const unsigned old = xb_add(&bar[XB_LSUB(b.x)], 1u);
;         if ((old & 31u) == 31u) xb_add(&bar[XB_LGEN(b.x)], 1u);
;         b.st[5] = old >> 5;
;     }
; }
.LBB0_730:
	s_and_b64 vcc, exec, s[46:47]
	s_cbranch_vccnz .LBB0_736
	v_mbcnt_lo_u32_b32 v0, -1, 0
	v_mbcnt_hi_u32_b32 v0, -1, v0
	s_nop 0
	v_cmp_eq_u32_e32 vcc, 0, v0
	s_and_saveexec_b64 s[0:1], vcc
	s_cbranch_execz .LBB0_735
	s_lshl_b32 s4, s23, 1
	s_add_u32 s2, s26, 0x6000
	s_addc_u32 s3, s27, 0
	s_add_u32 s2, s2, s4
	s_addc_u32 s3, s3, 0
	v_readlane_b32 s4, v254, 49
	s_add_i32 s5, s34, 3
	s_lshr_b32 s4, s4, 3
	s_lshl_b32 s4, s4, 2
	v_mov_b32_e32 v0, s4
	v_mov_b32_e32 v1, s5
	s_waitcnt vmcnt(0) lgkmcnt(0)
	global_store_dword v0, v1, s[2:3]
	v_mov_b32_e32 v0, s21
	ds_write_b32 v0, v1
	s_branch .Lxbf_end_S3
	s_nop 0
	s_nop 0
	s_nop 0
	s_nop 0
	s_nop 0
	s_nop 0
	s_nop 0
	s_nop 0
	s_nop 0
	s_nop 0
	s_nop 0
	s_nop 0
	s_nop 0
.Lxbf_end_S3:
.LBB0_735:
	s_or_b64 exec, exec, s[0:1]

; __device__ __forceinline__ unsigned xb_ld(unsigned* p)              { return __hip_atomic_load(p, __ATOMIC_RELAXED, __HIP_MEMORY_SCOPE_AGENT); }
; #define XB_SPIN(cond, bar) do { unsigned _sp = 0; while (cond) { __builtin_amdgcn_s_sleep(1); \
;     if ((++_sp & 255u) == 0u) { if (xb_ld(&(bar)[XB_TMO])) break; if (_sp > XB_SPIN_CAP) { atomicAdd(&(bar)[XB_TMO], 1u); break; } } } } while (0)
; __device__ __forceinline__ bool is_t0(int wave) { return wave == 0 && olane() == 0; }
; __device__ __forceinline__ void xcdl_wait_t0(const XcdBarrier& b) {
;     if (is_t0(b.wave)) {
;         unsigned* bar = b.bar; asm volatile("" : "+s"(bar));
;         const unsigned gen = b.st[5];
;         XB_SPIN(xb_ld(&bar[XB_LGEN(b.x)]) == gen, bar);
;         __builtin_amdgcn_fence(__ATOMIC_ACQUIRE, "agent");
;         asm volatile("s_waitcnt vmcnt(0)" ::: "memory");
;     }
; }
;     __device__ __forceinline__ void gate() const {
;         if (gate_cnt) psync_wait(gate_cnt, st.tmo, 0x900u);
;         if (gate_xcc) { xcdl_wait_t0(gb); asm volatile("s_waitcnt lgkmcnt(0)" ::: "memory"); __builtin_amdgcn_s_barrier(); asm volatile("" ::: "memory"); }
.LBB0_747:
	s_cmp_lg_u32 s62, s28
	s_cselect_b64 s[56:57], -1, 0
	s_cmp_eq_u32 s62, s28
	s_cselect_b64 s[50:51], -1, 0
	s_or_b64 s[0:1], s[66:67], s[56:57]
	s_or_b64 s[0:1], s[0:1], s[94:95]
	s_and_b64 vcc, exec, s[0:1]
	s_cbranch_vccnz .LBB0_764
	s_and_b64 vcc, exec, s[46:47]
	s_cbranch_vccnz .LBB0_763
	v_mbcnt_lo_u32_b32 v138, -1, 0
	v_mbcnt_hi_u32_b32 v138, -1, v138
	s_nop 0
	v_cmp_eq_u32_e32 vcc, 0, v138
	s_and_saveexec_b64 s[60:61], vcc
	s_cbranch_execz .LBB0_762
	s_lshl_b32 s29, s23, 1
	s_add_u32 s0, s26, 0x6000
	s_addc_u32 s1, s27, 0
	s_add_u32 s0, s0, s29
	s_addc_u32 s1, s1, 0
	v_mov_b32_e32 v138, s21
	ds_read_b32 v138, v138
	s_waitcnt vmcnt(0) lgkmcnt(0)
	v_readfirstlane_b32 s4, v138
	s_mov_b64 s[8:9], exec
	s_mov_b32 exec_lo, -1
	s_mov_b32 exec_hi, 0
	v_mbcnt_lo_u32_b32 v139, -1, 0
	v_lshlrev_b32_e32 v139, 2, v139
	v_mov_b32_e32 v140, s4
	s_mov_b32 s5, 0
.Lxbf_poll_S6:
	global_load_dword v141, v139, s[0:1] sc1
	s_waitcnt vmcnt(0)
	v_cmp_lt_u32_e32 vcc, v141, v140
	s_nop 1
	s_cmp_eq_u64 vcc, 0
	s_cbranch_scc1 .Lxbf_done_S6
	s_sleep 1
	s_add_u32 s5, s5, 1
	s_cmp_lt_u32 s5, 0x4000
	s_cbranch_scc1 .Lxbf_poll_S6
	v_mov_b32_e32 v141, 1
	v_mov_b32_e32 v139, 0x200
	global_store_dword v139, v141, s[26:27] sc1
.Lxbf_done_S6:
	s_waitcnt vmcnt(0)
	s_mov_b64 exec, s[8:9]
	s_branch .Lxbf_end_S6
	s_nop 0
	s_nop 0
	s_nop 0
	s_nop 0
	s_nop 0
	s_nop 0
	s_nop 0
	s_nop 0
	s_nop 0
	s_nop 0
	s_nop 0
	s_nop 0
	s_nop 0
	s_nop 0
	s_nop 0
	s_nop 0
	s_nop 0
	s_nop 0
	s_nop 0
	s_nop 0
	s_nop 0
	s_nop 0
	s_nop 0
	s_nop 0
	s_nop 0
	s_nop 0
	s_nop 0
	s_nop 0
	s_nop 0
	s_nop 0
	s_nop 0
	s_nop 0
	s_nop 0
	s_nop 0
	s_nop 0
	s_nop 0
	s_nop 0
	s_nop 0
	s_nop 0
	s_nop 0
	s_nop 0
	s_nop 0
	s_nop 0
.Lxbf_end_S6:
.LBB0_762:
	s_or_b64 exec, exec, s[60:61]

; __device__ __forceinline__ unsigned xb_ld(unsigned* p)              { return __hip_atomic_load(p, __ATOMIC_RELAXED, __HIP_MEMORY_SCOPE_AGENT); }
; #define XB_SPIN(cond, bar) do { unsigned _sp = 0; while (cond) { __builtin_amdgcn_s_sleep(1); \
;     if ((++_sp & 255u) == 0u) { if (xb_ld(&(bar)[XB_TMO])) break; if (_sp > XB_SPIN_CAP) { atomicAdd(&(bar)[XB_TMO], 1u); break; } } } } while (0)
; __device__ __forceinline__ bool is_t0(int wave) { return wave == 0 && olane() == 0; }
; __device__ __forceinline__ void xcdl_wait_t0(const XcdBarrier& b) {
;     if (is_t0(b.wave)) {
;         unsigned* bar = b.bar; asm volatile("" : "+s"(bar));
;         const unsigned gen = b.st[5];
;         XB_SPIN(xb_ld(&bar[XB_LGEN(b.x)]) == gen, bar);
;         __builtin_amdgcn_fence(__ATOMIC_ACQUIRE, "agent");
;         asm volatile("s_waitcnt vmcnt(0)" ::: "memory");
;     }
; }
;     __device__ __forceinline__ void gate() const {
;         if (gate_cnt) psync_wait(gate_cnt, st.tmo, 0x900u);
;         if (gate_xcc) { xcdl_wait_t0(gb); asm volatile("s_waitcnt lgkmcnt(0)" ::: "memory"); __builtin_amdgcn_s_barrier(); asm volatile("" ::: "memory"); }
.LBB0_823:
	s_cmp_lg_u32 s48, s28
	s_cselect_b64 s[56:57], -1, 0
	s_cmp_eq_u32 s48, s28
	s_cselect_b64 s[50:51], -1, 0
	s_or_b64 s[0:1], s[92:93], s[56:57]
	s_or_b64 s[0:1], s[0:1], s[94:95]
	s_and_b64 vcc, exec, s[0:1]
	s_cbranch_vccnz .LBB0_840
	s_and_b64 vcc, exec, s[46:47]
	s_cbranch_vccnz .LBB0_839
	v_mbcnt_lo_u32_b32 v138, -1, 0
	v_mbcnt_hi_u32_b32 v138, -1, v138
	s_nop 0
	v_cmp_eq_u32_e32 vcc, 0, v138
	s_and_saveexec_b64 s[62:63], vcc
	s_cbranch_execz .LBB0_838
	s_lshl_b32 s29, s23, 1
	s_add_u32 s0, s26, 0x6000
	s_addc_u32 s1, s27, 0
	s_add_u32 s0, s0, s29
	s_addc_u32 s1, s1, 0
	v_mov_b32_e32 v138, s21
	ds_read_b32 v138, v138
	s_waitcnt vmcnt(0) lgkmcnt(0)
	v_readfirstlane_b32 s8, v138
	s_mov_b64 s[36:37], exec
	s_mov_b32 exec_lo, -1
	s_mov_b32 exec_hi, 0
	v_mbcnt_lo_u32_b32 v139, -1, 0
	v_lshlrev_b32_e32 v139, 2, v139
	v_mov_b32_e32 v140, s8
	s_mov_b32 s9, 0
.Lxbf_poll_S7:
	global_load_dword v141, v139, s[0:1] sc1
	s_waitcnt vmcnt(0)
	v_cmp_lt_u32_e32 vcc, v141, v140
	s_nop 1
	s_cmp_eq_u64 vcc, 0
	s_cbranch_scc1 .Lxbf_done_S7
	s_sleep 1
	s_add_u32 s9, s9, 1
	s_cmp_lt_u32 s9, 0x4000
	s_cbranch_scc1 .Lxbf_poll_S7
	v_mov_b32_e32 v141, 1
	v_mov_b32_e32 v139, 0x200
	global_store_dword v139, v141, s[26:27] sc1
.Lxbf_done_S7:
	s_waitcnt vmcnt(0)
	s_mov_b64 exec, s[36:37]
	s_branch .Lxbf_end_S7
	s_nop 0
	s_nop 0
	s_nop 0
	s_nop 0
	s_nop 0
	s_nop 0
	s_nop 0
	s_nop 0
	s_nop 0
	s_nop 0
	s_nop 0
	s_nop 0
	s_nop 0
	s_nop 0
	s_nop 0
	s_nop 0
	s_nop 0
	s_nop 0
	s_nop 0
	s_nop 0
	s_nop 0
	s_nop 0
	s_nop 0
	s_nop 0
	s_nop 0
	s_nop 0
	s_nop 0
	s_nop 0
	s_nop 0
	s_nop 0
	s_nop 0
	s_nop 0
	s_nop 0
	s_nop 0
	s_nop 0
	s_nop 0
	s_nop 0
	s_nop 0
	s_nop 0
	s_nop 0
	s_nop 0
	s_nop 0
	s_nop 0
	s_nop 0
	s_nop 0
	s_nop 0
	s_nop 0
	s_nop 0
	s_nop 0
	s_nop 0
	s_nop 0
	s_nop 0
	s_nop 0
	s_nop 0
	s_nop 0
	s_nop 0
.Lxbf_end_S7:
.LBB0_838:
	s_or_b64 exec, exec, s[62:63]

; __device__ __forceinline__ unsigned xb_add(unsigned* p, unsigned v) { return __hip_atomic_fetch_add(p, v, __ATOMIC_RELAXED, __HIP_MEMORY_SCOPE_AGENT); }
; __device__ __forceinline__ bool is_t0(int wave) { return wave == 0 && olane() == 0; }
; __device__ __forceinline__ void xcdl_arrive(const XcdBarrier& b) {
;     if (is_t0(b.wave)) {
;         unsigned* bar = b.bar; asm volatile("" : "+s"(bar));
;         const unsigned old = xb_add(&bar[XB_LSUB(b.x)], 1u);
;         if ((old & 31u) == 31u) xb_add(&bar[XB_LGEN(b.x)], 1u);
;         b.st[5] = old >> 5;
;     }
; }
; __global__ void __launch_bounds__(512, 2) mk_fwd(Args args) {
;     ...
;         else if (splitb && (SPLIT_BAR & 2) && L + 1 < DEPTH) { asm volatile("s_waitcnt vmcnt(0)" ::: "memory"); __syncthreads(); xcdl_arrive(bar); }
.LBB0_898:
	s_waitcnt vmcnt(0)
	s_and_b64 vcc, exec, s[46:47]
	s_waitcnt vmcnt(0) lgkmcnt(0)
	s_barrier
	s_cbranch_vccnz .LBB0_904
	v_mbcnt_lo_u32_b32 v0, -1, 0
	v_mbcnt_hi_u32_b32 v0, -1, v0
	s_nop 0
	v_cmp_eq_u32_e32 vcc, 0, v0
	s_and_saveexec_b64 s[0:1], vcc
	s_cbranch_execz .LBB0_903
	s_lshl_b32 s4, s23, 1
	s_add_u32 s2, s26, 0x6000
	s_addc_u32 s3, s27, 0
	s_add_u32 s2, s2, s4
	s_addc_u32 s3, s3, 0
	v_readlane_b32 s4, v254, 49
	s_add_i32 s5, s34, 4
	s_lshr_b32 s4, s4, 3
	s_lshl_b32 s4, s4, 2
	v_mov_b32_e32 v0, s4
	v_mov_b32_e32 v1, s5
	s_waitcnt vmcnt(0) lgkmcnt(0)
	global_store_dword v0, v1, s[2:3]
	v_mov_b32_e32 v0, s21
	ds_write_b32 v0, v1
